# baseline (speedup 1.0000x reference)
; template <int MODE>
; DI void hgrn_item2(const u16* PROJ, int tokbase, int dir, int h, int layer, const float* hgrn_lb, float* Sg, float* Pg,
;                    u16* OH, const float* norm_g, char* lds) {
;     ...
; #pragma unroll
;     for (int e = 0; e < 2; ++e) {
; #pragma unroll
;       for (int q4 = 0; q4 < 4; ++q4) { const int k0 = kb * 32 + 8 * q4 + 4 * hi;
;         const float4 er = *reinterpret_cast<const float4*>(lds + HL_ER + k0 * 4);
;         S[e][4 * q4] *= er.x; S[e][4 * q4 + 1] *= er.y; S[e][4 * q4 + 2] *= er.z; S[e][4 * q4 + 3] *= er.w;
;         if (MODE == 1) *reinterpret_cast<uint2*>(lds + HL_ST + ((vbs + e) * 32 + r32) * 272 + k0 * 2) = pack4(S[e][4 * q4], S[e][4 * q4 + 1], S[e][4 * q4 + 2], S[e][4 * q4 + 3]); } }
;     f32x16 oa = {0.f, 0.f, 0.f, 0.f, 0.f, 0.f, 0.f, 0.f, 0.f, 0.f, 0.f, 0.f, 0.f, 0.f, 0.f, 0.f};
;     const int vb = wid & 3, tb2 = wid >> 2;
;     if (MODE == 1) {
;       __syncthreads();
; #pragma unroll
;       for (int d0 = 0; d0 < 8; ++d0) {
;         const bf16x8 a = *reinterpret_cast<const bf16x8*>(lds + HL_ST + (vb * 32 + r32) * 272 + d0 * 32 + hi * 16);
;         const bf16x8 b = *reinterpret_cast<const bf16x8*>(lds + HL_QT + (tb2 * 32 + r32) * 272 + d0 * 32 + hi * 16);
;         oa = __builtin_amdgcn_mfma_f32_32x32x16_bf16(a, b, oa, 0, 0, 0); }
; #pragma unroll
;       for (int s0 = 0; s0 < 4; ++s0) {
;         const bf16x8 a = *reinterpret_cast<const bf16x8*>(lds + HL_VT + (vb * 32 + r32) * 144 + (((s0 * 2 + hi) ^ ((vb * 2 + (r32 >> 4)) & 7)) << 4));
;         const bf16x8 b = *reinterpret_cast<const bf16x8*>(lds + HL_RAWQ + (tb2 * 32 + r32) * 144 + s0 * 32 + hi * 16);
;         oa = __builtin_amdgcn_mfma_f32_32x32x16_bf16(a, b, oa, 0, 0, 0); }
;     }
; #pragma unroll
;     for (int e = 0; e < 2; ++e) {
; #pragma unroll
;       for (int s0 = 0; s0 < 4; ++s0) {
;         const bf16x8 a = *reinterpret_cast<const bf16x8*>(lds + HL_KT + (kb * 32 + r32) * 144 + s0 * 32 + hi * 16);
;         const bf16x8 b = *reinterpret_cast<const bf16x8*>(lds + HL_VT + ((vbs + e) * 32 + r32) * 144 + (((s0 * 2 + hi) ^ (((vbs + e) * 2 + (r32 >> 4)) & 7)) << 4));
;         S[e] = __builtin_amdgcn_mfma_f32_32x32x16_bf16(a, b, S[e], 0, 0, 0); }
; #pragma unroll
;       for (int q4 = 0; q4 < 4; ++q4) { const float4 eb = *reinterpret_cast<const float4*>(lds + HL_EB + (kb * 32 + 8 * q4 + 4 * hi) * 4);
.LBB0_75:
	s_or_b64 exec, exec, vcc
	ds_read_b128 v[0:3], v169
	v_add_u32_e32 v6, v134, v135
	v_add_u32_e32 v10, v134, v136
	v_add_u32_e32 v14, v134, v137
	v_add_u32_e32 v80, v129, v127
	s_waitcnt lgkmcnt(0)
	v_pk_mul_f32 v[0:1], v[44:45], v[0:1]
	v_pk_mul_f32 v[2:3], v[42:43], v[2:3]
	v_cvt_pk_bf16_f32 v4, v0, v1
	v_add_u32_e32 v116, s90, v141
	v_cvt_pk_bf16_f32 v5, v2, v3
	ds_write_b64 v6, v[4:5]
	ds_read_b128 v[4:7], v170
	v_cndmask_b32_e64 v116, v116, v126, s[98:99]
	v_add_u32_e32 v116, s88, v116
	v_ashrrev_i32_e32 v117, 31, v116
	v_lshlrev_b64 v[116:117], 11, v[116:117]
	s_waitcnt lgkmcnt(0)
	v_pk_mul_f32 v[4:5], v[40:41], v[4:5]
	v_pk_mul_f32 v[6:7], v[38:39], v[6:7]
	v_cvt_pk_bf16_f32 v8, v4, v5
	v_lshl_add_u64 v[116:117], v[94:95], 0, v[116:117]
	v_and_b32_e32 v214, 32, v232
	v_lshrrev_b32_e32 v214, 2, v214
	v_mov_b32_e32 v215, 0
	v_lshl_add_u64 v[216:217], v[116:117], 0, v[214:215]
	v_cvt_pk_bf16_f32 v9, v6, v7
	ds_write_b64 v10, v[8:9]
	ds_read_b128 v[8:11], v171
	s_and_b64 vcc, exec, s[82:83]
	s_mov_b64 s[6:7], -1
	s_waitcnt lgkmcnt(0)
	v_pk_mul_f32 v[8:9], v[46:47], v[8:9]
	v_pk_mul_f32 v[10:11], v[36:37], v[10:11]
	v_cvt_pk_bf16_f32 v12, v8, v9
	v_add_u32_e32 v36, v134, v138
	v_cvt_pk_bf16_f32 v13, v10, v11
	ds_write_b64 v14, v[12:13]
	ds_read_b128 v[12:15], v172
	s_waitcnt lgkmcnt(0)
	v_pk_mul_f32 v[12:13], v[34:35], v[12:13]
	v_pk_mul_f32 v[14:15], v[32:33], v[14:15]
	v_cvt_pk_bf16_f32 v32, v12, v13
	s_nop 0
	v_cvt_pk_bf16_f32 v33, v14, v15
	ds_write_b64 v36, v[32:33]
	ds_read_b128 v[32:35], v169
	v_add_u32_e32 v36, v139, v135
	s_waitcnt lgkmcnt(0)
	v_pk_mul_f32 v[16:17], v[16:17], v[32:33]
	v_pk_mul_f32 v[18:19], v[18:19], v[34:35]
	v_cvt_pk_bf16_f32 v32, v16, v17
	s_nop 0
	v_cvt_pk_bf16_f32 v33, v18, v19
	ds_write_b64 v36, v[32:33]
	ds_read_b128 v[32:35], v170
	v_add_u32_e32 v36, v139, v136
	s_waitcnt lgkmcnt(0)
	v_pk_mul_f32 v[20:21], v[20:21], v[32:33]
	v_pk_mul_f32 v[22:23], v[22:23], v[34:35]
	v_cvt_pk_bf16_f32 v32, v20, v21
	s_nop 0
	v_cvt_pk_bf16_f32 v33, v22, v23
	ds_write_b64 v36, v[32:33]
	ds_read_b128 v[32:35], v171
	v_add_u32_e32 v36, v139, v137
	s_waitcnt lgkmcnt(0)
	v_pk_mul_f32 v[24:25], v[24:25], v[32:33]
	v_pk_mul_f32 v[26:27], v[26:27], v[34:35]
	v_cvt_pk_bf16_f32 v32, v24, v25
	s_nop 0
	v_cvt_pk_bf16_f32 v33, v26, v27
	ds_write_b64 v36, v[32:33]
	ds_read_b128 v[32:35], v172
	v_add_u32_e32 v36, v139, v138
	s_waitcnt lgkmcnt(0)
	v_pk_mul_f32 v[28:29], v[28:29], v[32:33]
	v_pk_mul_f32 v[30:31], v[30:31], v[34:35]
	v_cvt_pk_bf16_f32 v32, v28, v29
	s_nop 0
	v_cvt_pk_bf16_f32 v33, v30, v31
	ds_write_b64 v36, v[32:33]
	s_waitcnt lgkmcnt(0)
	s_barrier
	ds_read_b128 v[32:35], v153
	ds_read_b128 v[36:39], v80 offset:51200
	ds_read_b128 v[72:75], v159
	ds_read_b128 v[76:79], v160 offset:32768
	s_waitcnt lgkmcnt(0)
	v_mfma_f32_32x32x16_bf16 v[0:15], v[72:75], v[76:79], v[0:15]
	ds_read_b128 v[76:79], v164 offset:32768
	v_mfma_f32_32x32x16_bf16 v[32:47], v[32:35], v[36:39], 0
	s_waitcnt lgkmcnt(0)
	v_mfma_f32_32x32x16_bf16 v[16:31], v[72:75], v[76:79], v[16:31]
	ds_read_b128 v[72:75], v153 offset:32
	ds_read_b128 v[76:79], v80 offset:51232
	s_waitcnt lgkmcnt(0)
	v_mfma_f32_32x32x16_bf16 v[32:47], v[72:75], v[76:79], v[32:47]
	ds_read_b128 v[72:75], v159 offset:32
	ds_read_b128 v[76:79], v161 offset:32768
	s_waitcnt lgkmcnt(0)
	v_mfma_f32_32x32x16_bf16 v[0:15], v[72:75], v[76:79], v[0:15]
	ds_read_b128 v[76:79], v165 offset:32768
	s_waitcnt lgkmcnt(0)
	v_mfma_f32_32x32x16_bf16 v[16:31], v[72:75], v[76:79], v[16:31]
	ds_read_b128 v[72:75], v153 offset:64
	ds_read_b128 v[76:79], v80 offset:51264
	s_waitcnt lgkmcnt(0)
	v_mfma_f32_32x32x16_bf16 v[32:47], v[72:75], v[76:79], v[32:47]
	ds_read_b128 v[72:75], v159 offset:64
	ds_read_b128 v[76:79], v162 offset:32768
	s_waitcnt lgkmcnt(0)
	v_mfma_f32_32x32x16_bf16 v[0:15], v[72:75], v[76:79], v[0:15]
	ds_read_b128 v[76:79], v166 offset:32768
	s_waitcnt lgkmcnt(0)
	v_mfma_f32_32x32x16_bf16 v[16:31], v[72:75], v[76:79], v[16:31]
	ds_read_b128 v[72:75], v153 offset:96
	ds_read_b128 v[76:79], v80 offset:51296
	s_waitcnt lgkmcnt(0)
	v_mfma_f32_32x32x16_bf16 v[32:47], v[72:75], v[76:79], v[32:47]
	ds_read_b128 v[72:75], v159 offset:96
	ds_read_b128 v[76:79], v163 offset:32768
	s_waitcnt lgkmcnt(0)
	v_mfma_f32_32x32x16_bf16 v[0:15], v[72:75], v[76:79], v[0:15]
	ds_read_b128 v[76:79], v167 offset:32768
	s_waitcnt lgkmcnt(0)
	v_mfma_f32_32x32x16_bf16 v[16:31], v[72:75], v[76:79], v[16:31]
	ds_read_b128 v[72:75], v153 offset:128
	ds_read_b128 v[76:79], v80 offset:51328
	s_waitcnt lgkmcnt(0)
	v_mfma_f32_32x32x16_bf16 v[32:47], v[72:75], v[76:79], v[32:47]
	ds_read_b128 v[72:75], v153 offset:160
	ds_read_b128 v[76:79], v80 offset:51360
	s_waitcnt lgkmcnt(0)
	v_mfma_f32_32x32x16_bf16 v[32:47], v[72:75], v[76:79], v[32:47]
	ds_read_b128 v[72:75], v153 offset:192
	ds_read_b128 v[76:79], v80 offset:51392
	s_waitcnt lgkmcnt(0)
	v_mfma_f32_32x32x16_bf16 v[32:47], v[72:75], v[76:79], v[32:47]
	ds_read_b128 v[72:75], v153 offset:224
	ds_read_b128 v[76:79], v80 offset:51424
	s_waitcnt lgkmcnt(0)
	v_mfma_f32_32x32x16_bf16 v[32:47], v[72:75], v[76:79], v[32:47]
	ds_read_b128 v[72:75], v154 offset:32768
	ds_read_b128 v[76:79], v155
	s_waitcnt lgkmcnt(0)
	v_mfma_f32_32x32x16_bf16 v[32:47], v[72:75], v[76:79], v[32:47]
	ds_read_b128 v[72:75], v156 offset:32768
	ds_read_b128 v[76:79], v155 offset:32
	s_waitcnt lgkmcnt(0)
	v_mfma_f32_32x32x16_bf16 v[32:47], v[72:75], v[76:79], v[32:47]
	ds_read_b128 v[72:75], v157 offset:32768
	ds_read_b128 v[76:79], v155 offset:64
	s_waitcnt lgkmcnt(0)
	v_mfma_f32_32x32x16_bf16 v[32:47], v[72:75], v[76:79], v[32:47]
	ds_read_b128 v[174:177], v158 offset:32768
	ds_read_b128 v[178:181], v155 offset:96
	ds_read_b128 v[72:75], v168
	ds_read_b128 v[76:79], v168 offset:32
	ds_read_b128 v[80:83], v168 offset:64
	ds_read_b128 v[84:87], v168 offset:96
	s_waitcnt lgkmcnt(4)
	v_mfma_f32_32x32x16_bf16 v[32:47], v[174:177], v[178:181], v[32:47]
	s_cbranch_vccnz .LBB0_79
; template <int MODE>
; DI void hgrn_item2(const u16* PROJ, int tokbase, int dir, int h, int layer, const float* hgrn_lb, float* Sg, float* Pg,
;                    u16* OH, const float* norm_g, char* lds) {
;     ...
;         float ss = 0.f;
; #pragma unroll
;         for (int q4 = 0; q4 < 4; ++q4) { const uint2 t8 = pf_t[q4];
;           oa[4 * q4] += __uint_as_float(t8.x << 16); oa[4 * q4 + 1] += __uint_as_float(t8.x & 0xffff0000u);
;           oa[4 * q4 + 2] += __uint_as_float(t8.y << 16); oa[4 * q4 + 3] += __uint_as_float(t8.y & 0xffff0000u);
;           ss += oa[4 * q4] * oa[4 * q4] + oa[4 * q4 + 1] * oa[4 * q4 + 1] + oa[4 * q4 + 2] * oa[4 * q4 + 2] + oa[4 * q4 + 3] * oa[4 * q4 + 3]; }
;         ss += __int_as_float(__builtin_amdgcn_ds_bpermute((lane ^ 32) << 2, __float_as_int(ss)));
;         if (hi == 0) reinterpret_cast<float*>(lds + HL_SS)[vb * 64 + t] = ss;
	s_waitcnt vmcnt(7)
	v_lshlrev_b32_e32 v173, 16, v100
	s_waitcnt vmcnt(6)
	v_lshlrev_b32_e32 v174, 16, v102
	s_nop 6
	v_add_f32_e32 v189, v32, v173
	v_and_b32_e32 v173, 0xffff0000, v100
	v_add_f32_e32 v185, v36, v174
	v_and_b32_e32 v174, 0xffff0000, v102
	v_add_f32_e32 v188, v33, v173
	v_lshlrev_b32_e32 v173, 16, v101
	v_add_f32_e32 v184, v37, v174
	v_lshlrev_b32_e32 v174, 16, v103
	v_add_f32_e32 v187, v34, v173
	v_and_b32_e32 v173, 0xffff0000, v101
	v_add_f32_e32 v183, v38, v174
	v_and_b32_e32 v174, 0xffff0000, v103
	v_add_f32_e32 v186, v35, v173
	v_mul_f32_e32 v173, v188, v188
	v_add_f32_e32 v182, v39, v174
	v_mul_f32_e32 v174, v184, v184
	v_fmac_f32_e32 v173, v189, v189
	v_fmac_f32_e32 v174, v185, v185
	v_fmac_f32_e32 v173, v187, v187
	v_fmac_f32_e32 v174, v183, v183
	v_fmac_f32_e32 v173, v186, v186
	v_fmac_f32_e32 v174, v182, v182
	v_add_f32_e32 v173, v173, v174
	s_waitcnt vmcnt(5)
	v_lshlrev_b32_e32 v174, 16, v104
	v_add_f32_e32 v181, v40, v174
	v_and_b32_e32 v174, 0xffff0000, v104
	v_add_f32_e32 v180, v41, v174
	v_lshlrev_b32_e32 v174, 16, v105
	v_add_f32_e32 v179, v42, v174
	v_and_b32_e32 v174, 0xffff0000, v105
	v_add_f32_e32 v178, v43, v174
	v_mul_f32_e32 v174, v180, v180
	v_fmac_f32_e32 v174, v181, v181
	v_fmac_f32_e32 v174, v179, v179
	v_fmac_f32_e32 v174, v178, v178
	v_add_f32_e32 v175, v174, v173
	s_waitcnt vmcnt(4)
	v_lshlrev_b32_e32 v173, 16, v106
	v_add_f32_e32 v177, v44, v173
	v_and_b32_e32 v173, 0xffff0000, v106
	v_add_f32_e32 v176, v45, v173
	v_lshlrev_b32_e32 v173, 16, v107
	v_mul_f32_e32 v190, v176, v176
	v_add_f32_e32 v174, v46, v173
	v_and_b32_e32 v173, 0xffff0000, v107
	v_fmac_f32_e32 v190, v177, v177
	v_add_f32_e32 v173, v47, v173
	v_fmac_f32_e32 v190, v174, v174
	v_fmac_f32_e32 v190, v173, v173
	v_add_f32_e32 v175, v190, v175
	ds_bpermute_b32 v190, v130, v175
	s_and_saveexec_b64 s[6:7], s[48:49]
	s_cbranch_execz .LBB0_78
	s_waitcnt lgkmcnt(0)
	v_add_f32_e32 v175, v175, v190
	ds_write_b32 v132, v175
; DI uint2 pack4(float a, float b, float c, float d) { return make_uint2(cvtpk(a, b), cvtpk(c, d)); }
; template <int MODE>
; DI void hgrn_item2(const u16* PROJ, int tokbase, int dir, int h, int layer, const float* hgrn_lb, float* Sg, float* Pg,
;                    u16* OH, const float* norm_g, char* lds) {
;     ...
;     if (MODE == 1) {
;       const int t = tb2 * 32 + r32, p_ = c * 64 + t; const int tok = tokbase + (dir ? 511 - p_ : p_);
;       u16* op = OH + (size_t)tok * 1024 + h * 128 + vb * 32 + 4 * hi;
;       if (dir == 0) {
; #pragma unroll
;         for (int q4 = 0; q4 < 4; ++q4) *reinterpret_cast<uint2*>(op + 8 * q4) = pack4(oa[4 * q4], oa[4 * q4 + 1], oa[4 * q4 + 2], oa[4 * q4 + 3]);
;         __syncthreads();
;       } else {
;         float ss = 0.f;
; #pragma unroll
;         for (int q4 = 0; q4 < 4; ++q4) { const uint2 t8 = pf_t[q4];
;           oa[4 * q4] += __uint_as_float(t8.x << 16); oa[4 * q4 + 1] += __uint_as_float(t8.x & 0xffff0000u);
;           oa[4 * q4 + 2] += __uint_as_float(t8.y << 16); oa[4 * q4 + 3] += __uint_as_float(t8.y & 0xffff0000u);
;           ss += oa[4 * q4] * oa[4 * q4] + oa[4 * q4 + 1] * oa[4 * q4 + 1] + oa[4 * q4 + 2] * oa[4 * q4 + 2] + oa[4 * q4 + 3] * oa[4 * q4 + 3]; }
;         ss += __int_as_float(__builtin_amdgcn_ds_bpermute((lane ^ 32) << 2, __float_as_int(ss)));
;         if (hi == 0) reinterpret_cast<float*>(lds + HL_SS)[vb * 64 + t] = ss;
;         __syncthreads();
;         const float* ssp = reinterpret_cast<const float*>(lds + HL_SS) + t;
;         const float rn = rsqrtf((ssp[0] + ssp[64] + ssp[128] + ssp[192]) * (1.f / 128.f) + EPS);
; #pragma unroll
;         for (int q4 = 0; q4 < 4; ++q4) { const int cv = h * 128 + vb * 32 + 4 * hi + 8 * q4;
;           const uint2 hg = pf_g[q4]; const float4 ng = *reinterpret_cast<const float4*>(norm_g + cv);
;           const float h0 = __uint_as_float(hg.x << 16), h1 = __uint_as_float(hg.x & 0xffff0000u), h2 = __uint_as_float(hg.y << 16), h3 = __uint_as_float(hg.y & 0xffff0000u);
;           *reinterpret_cast<uint2*>(op + 8 * q4) = pack4(oa[4 * q4] * rn * ng.x * (h0 * sigm(h0)), oa[4 * q4 + 1] * rn * ng.y * (h1 * sigm(h1)),
;                                                          oa[4 * q4 + 2] * rn * ng.z * (h2 * sigm(h2)), oa[4 * q4 + 3] * rn * ng.w * (h3 * sigm(h3))); }
;       }
.LBB0_78:
	s_or_b64 exec, exec, s[6:7]
	s_waitcnt lgkmcnt(0)
	s_barrier
	ds_read2st64_b32 v[190:191], v131 offset1:1
	s_waitcnt vmcnt(3)
	v_lshlrev_b32_e32 v194, 16, v114
	v_and_b32_e32 v195, 0xffff0000, v114
	v_lshlrev_b32_e32 v196, 16, v115
	v_and_b32_e32 v197, 0xffff0000, v115
	s_waitcnt lgkmcnt(0)
	v_add_f32_e32 v175, v190, v191
	ds_read2st64_b32 v[190:191], v131 offset0:2 offset1:3
	s_mov_b64 s[6:7], 0
	s_waitcnt lgkmcnt(0)
	v_add_f32_e32 v175, v175, v190
	v_add_f32_e32 v175, v175, v191
	v_fmamk_f32 v175, v175, 0x3c000000, v233
	v_cmp_gt_f32_e32 vcc, s91, v175
	v_mul_f32_e32 v190, 0x4b800000, v175
	s_nop 0
	v_cndmask_b32_e32 v175, v175, v190, vcc
	v_rsq_f32_e32 v175, v175
	s_nop 0
	v_mul_f32_e32 v190, 0x45800000, v175
	v_cndmask_b32_e32 v175, v175, v190, vcc
	v_mul_f32_e32 v189, v189, v175
	v_mul_f32_e32 v188, v188, v175
	v_mul_f32_e32 v187, v187, v175
	v_mul_f32_e32 v186, v186, v175
	v_mul_f32_e32 v185, v185, v175
	v_mul_f32_e32 v184, v184, v175
	v_mul_f32_e32 v183, v183, v175
	v_mul_f32_e32 v182, v182, v175
	v_mul_f32_e32 v181, v181, v175
	v_mul_f32_e32 v180, v180, v175
	v_mul_f32_e32 v179, v179, v175
	v_mul_f32_e32 v178, v178, v175
	v_mul_f32_e32 v177, v177, v175
	v_mul_f32_e32 v176, v176, v175
	v_mul_f32_e32 v174, v174, v175
	v_mul_f32_e32 v173, v173, v175
	s_waitcnt vmcnt(0)
	v_mul_f32_e32 v189, v198, v189
	v_mul_f32_e32 v190, 0xbfb8aa3b, v194
	v_exp_f32_e32 v190, v190
	v_mul_f32_e32 v188, v199, v188
	v_mul_f32_e32 v187, v200, v187
	v_mul_f32_e32 v186, v201, v186
	v_add_f32_e32 v190, 1.0, v190
	v_rcp_f32_e32 v190, v190
	v_and_b32_e32 v191, 0xffff0000, v112
	v_lshlrev_b32_e32 v192, 16, v113
	v_and_b32_e32 v193, 0xffff0000, v113
	v_mul_f32_e32 v190, v190, v194
	v_mul_f32_e32 v189, v190, v189
	v_mul_f32_e32 v190, 0xbfb8aa3b, v195
	v_exp_f32_e32 v190, v190
	s_nop 0
	v_add_f32_e32 v190, 1.0, v190
	v_rcp_f32_e32 v190, v190
	s_nop 0
	v_mul_f32_e32 v190, v190, v195
	v_mul_f32_e32 v188, v190, v188
	v_mul_f32_e32 v190, 0xbfb8aa3b, v196
	v_exp_f32_e32 v190, v190
	s_nop 0
	v_add_f32_e32 v190, 1.0, v190
	v_rcp_f32_e32 v190, v190
	s_nop 0
	v_mul_f32_e32 v190, v190, v196
	v_mul_f32_e32 v187, v190, v187
	v_mul_f32_e32 v190, 0xbfb8aa3b, v197
	v_exp_f32_e32 v190, v190
	s_nop 0
	v_add_f32_e32 v190, 1.0, v190
	v_rcp_f32_e32 v190, v190
	s_nop 0
	v_mul_f32_e32 v190, v190, v197
	v_mul_f32_e32 v190, v190, v186
	v_cvt_pk_bf16_f32 v218, v189, v188
	v_cvt_pk_bf16_f32 v219, v187, v190
	v_lshlrev_b32_e32 v190, 16, v112
	v_mul_f32_e32 v185, v185, v202
	v_mul_f32_e32 v186, 0xbfb8aa3b, v190
	v_exp_f32_e32 v186, v186
	v_mul_f32_e32 v184, v184, v203
	v_mul_f32_e32 v183, v183, v204
	v_mul_f32_e32 v182, v182, v205
	v_add_f32_e32 v186, 1.0, v186
	v_rcp_f32_e32 v186, v186
	v_and_b32_e32 v187, 0xffff0000, v110
	v_lshlrev_b32_e32 v188, 16, v111
	v_and_b32_e32 v189, 0xffff0000, v111
	v_mul_f32_e32 v186, v186, v190
	v_mul_f32_e32 v185, v186, v185
	v_mul_f32_e32 v186, 0xbfb8aa3b, v191
	v_exp_f32_e32 v186, v186
	s_nop 0
	v_add_f32_e32 v186, 1.0, v186
	v_rcp_f32_e32 v186, v186
	s_nop 0
	v_mul_f32_e32 v186, v186, v191
	v_mul_f32_e32 v184, v186, v184
	v_mul_f32_e32 v186, 0xbfb8aa3b, v192
	v_exp_f32_e32 v186, v186
	s_nop 0
	v_add_f32_e32 v186, 1.0, v186
	v_rcp_f32_e32 v186, v186
	s_nop 0
	v_mul_f32_e32 v186, v186, v192
	v_mul_f32_e32 v183, v186, v183
	v_mul_f32_e32 v186, 0xbfb8aa3b, v193
	v_exp_f32_e32 v186, v186
	s_nop 0
	v_add_f32_e32 v186, 1.0, v186
	v_rcp_f32_e32 v186, v186
	s_nop 0
	v_mul_f32_e32 v186, v186, v193
	v_mul_f32_e32 v186, v186, v182
	v_cvt_pk_bf16_f32 v220, v185, v184
	v_cvt_pk_bf16_f32 v221, v183, v186
	s_nop 1
	v_permlane32_swap_b32_e32 v218, v220
	v_permlane32_swap_b32_e32 v219, v221
	s_nop 0
	global_store_dwordx4 v[216:217], v[218:221], off
	v_lshlrev_b32_e32 v186, 16, v110
	v_mul_f32_e32 v181, v181, v206
	v_mul_f32_e32 v182, 0xbfb8aa3b, v186
	v_exp_f32_e32 v182, v182
	v_mul_f32_e32 v180, v180, v207
	v_mul_f32_e32 v179, v179, v208
	v_mul_f32_e32 v178, v178, v209
	v_add_f32_e32 v182, 1.0, v182
	v_rcp_f32_e32 v182, v182
	v_and_b32_e32 v183, 0xffff0000, v108
	v_lshlrev_b32_e32 v184, 16, v109
	v_and_b32_e32 v185, 0xffff0000, v109
	v_mul_f32_e32 v182, v182, v186
	v_mul_f32_e32 v181, v182, v181
	v_mul_f32_e32 v182, 0xbfb8aa3b, v187
	v_exp_f32_e32 v182, v182
	s_nop 0
	v_add_f32_e32 v182, 1.0, v182
	v_rcp_f32_e32 v182, v182
	s_nop 0
	v_mul_f32_e32 v182, v182, v187
	v_mul_f32_e32 v180, v182, v180
	v_mul_f32_e32 v182, 0xbfb8aa3b, v188
	v_exp_f32_e32 v182, v182
	s_nop 0
	v_add_f32_e32 v182, 1.0, v182
	v_rcp_f32_e32 v182, v182
	s_nop 0
	v_mul_f32_e32 v182, v182, v188
	v_mul_f32_e32 v179, v182, v179
	v_mul_f32_e32 v182, 0xbfb8aa3b, v189
	v_exp_f32_e32 v182, v182
	s_nop 0
	v_add_f32_e32 v182, 1.0, v182
	v_rcp_f32_e32 v182, v182
	s_nop 0
	v_mul_f32_e32 v182, v182, v189
	v_mul_f32_e32 v182, v182, v178
	v_cvt_pk_bf16_f32 v222, v181, v180
	v_cvt_pk_bf16_f32 v223, v179, v182
	v_lshlrev_b32_e32 v182, 16, v108
	v_mul_f32_e32 v177, v177, v210
	v_mul_f32_e32 v178, 0xbfb8aa3b, v182
	v_exp_f32_e32 v178, v178
	v_mul_f32_e32 v176, v176, v211
	v_mul_f32_e32 v174, v174, v212
	v_mul_f32_e32 v173, v173, v213
	v_add_f32_e32 v178, 1.0, v178
	v_rcp_f32_e32 v178, v178
	s_nop 0
	v_mul_f32_e32 v178, v178, v182
	v_mul_f32_e32 v177, v178, v177
	v_mul_f32_e32 v178, 0xbfb8aa3b, v183
	v_exp_f32_e32 v178, v178
	s_nop 0
	v_add_f32_e32 v178, 1.0, v178
	v_rcp_f32_e32 v178, v178
	s_nop 0
	v_mul_f32_e32 v178, v178, v183
	v_mul_f32_e32 v176, v178, v176
	v_mul_f32_e32 v178, 0xbfb8aa3b, v184
	v_exp_f32_e32 v178, v178
	s_nop 0
	v_add_f32_e32 v178, 1.0, v178
	v_rcp_f32_e32 v178, v178
	s_nop 0
	v_mul_f32_e32 v178, v178, v184
	v_mul_f32_e32 v178, v178, v174
	v_mul_f32_e32 v174, 0xbfb8aa3b, v185
	v_exp_f32_e32 v174, v174
	s_nop 0
	v_add_f32_e32 v174, 1.0, v174
	v_rcp_f32_e32 v174, v174
	s_nop 0
	v_mul_f32_e32 v174, v174, v185
	v_mul_f32_e32 v173, v174, v173
	v_cvt_pk_bf16_f32 v224, v177, v176
	v_cvt_pk_bf16_f32 v225, v178, v173
	s_nop 1
	v_permlane32_swap_b32_e32 v222, v224
	v_permlane32_swap_b32_e32 v223, v225
	s_nop 0
	global_store_dwordx4 v[216:217], v[222:225], off offset:32
.LBB0_79:
	s_and_b64 vcc, exec, s[6:7]
	s_cbranch_vccz .LBB0_66
	s_nop 7
	v_cvt_pk_bf16_f32 v32, v32, v33
	v_cvt_pk_bf16_f32 v33, v34, v35
	v_cvt_pk_bf16_f32 v34, v36, v37
	v_cvt_pk_bf16_f32 v35, v38, v39
	v_cvt_pk_bf16_f32 v36, v40, v41
	v_cvt_pk_bf16_f32 v37, v42, v43
	v_cvt_pk_bf16_f32 v38, v44, v45
	v_cvt_pk_bf16_f32 v39, v46, v47
	s_nop 1
	v_permlane32_swap_b32_e32 v32, v34
	v_permlane32_swap_b32_e32 v33, v35
	v_permlane32_swap_b32_e32 v36, v38
	v_permlane32_swap_b32_e32 v37, v39
	s_nop 1
	global_store_dwordx4 v[216:217], v[32:35], off
	global_store_dwordx4 v[216:217], v[36:39], off offset:32
	s_waitcnt lgkmcnt(0)
	s_barrier
	s_branch .LBB0_66
